# gate/up GEMM tile order: M-tile group of the per-XCD sweep 2 -> 8 (8 A-tiles x 4 B-tiles per round per XCD)
# baseline (speedup 1.0000x reference)
.LBB0_153:
	s_and_b32 s5, s2, 7
	s_mul_i32 s6, s5, 0x60
	v_writelane_b32 v245, s6, 5
	s_or_b32 s6, s6, s82
	s_mul_i32 s4, s9, s8
	s_mul_hi_u32 s7, s6, 0x15555556
	s_lshl_b32 s9, s85, 18
	s_lshl_b32 s8, s7, 1
	s_mul_i32 s7, s7, 12
	s_and_b32 s9, s9, 0x3f80000
	s_sub_i32 s6, s6, s7
	v_readlane_b32 s7, v245, 3
	v_writelane_b32 v245, s9, 6
	s_lshl_b32 s9, s85, 7
	s_lshl_b32 s10, s83, 17
	s_bfe_u32 s7, s7, 0x10003
	v_writelane_b32 v245, s10, 7
	s_and_b32 s9, s9, 0xf00
	v_writelane_b32 v245, s9, 8
	s_lshl_b32 s9, s7, 8
	v_writelane_b32 v245, s9, 9
	s_mul_i32 s4, s4, s84
	s_lshl_b32 s19, s7, 19
	v_writelane_b32 v245, s4, 10
	s_lshr_b32 s4, s83, 5
	s_lshl_b32 s9, s83, 1
	v_writelane_b32 v245, s9, 11
	s_cmpk_lt_u32 s83, 0x80
	s_movk_i32 s9, 0xa1
	s_cselect_b32 s9, s9, 0xa0
	v_writelane_b32 v245, s9, 12
	s_cselect_b32 s9, 33, 32
	v_writelane_b32 v245, s9, 13
	s_or_b32 s9, s9, 0x50
	v_writelane_b32 v245, s9, 14
	s_add_i32 s63, 0, 0x10000
	v_readlane_b32 s18, v245, 2
	s_lshl_b32 s9, s18, 5
	v_writelane_b32 v245, s9, 15
	s_lshl_b32 s9, s18, 4
	s_lshl_b32 s10, s18, 3
	s_and_b32 s9, s9, 48
	v_writelane_b32 v245, s9, 16
	s_and_b32 s9, s10, 0x1fffffe0
	v_writelane_b32 v245, s10, 17
	s_addk_i32 s9, 0x400
	v_writelane_b32 v245, s9, 18
	s_mul_i32 s9, s4, 0xc00000
	v_writelane_b32 v245, s9, 19
	s_lshl_b32 s9, s18, 10
	s_add_i32 s10, s63, s9
	s_add_i32 s11, s10, 0x2000
	v_writelane_b32 v245, s11, 20
	s_add_i32 s11, s10, 0x4000
	v_writelane_b32 v245, s11, 21
	v_writelane_b32 v245, s10, 22
	s_addk_i32 s10, 0x6000
	s_add_i32 s64, s9, 0
	v_writelane_b32 v245, s10, 23
	s_add_i32 s9, s64, 0x2000
	v_writelane_b32 v245, s9, 24
	s_lshl_b32 s9, s18, 12
	v_writelane_b32 v245, s9, 25
	s_add_i32 s52, s63, s9
	s_lshl_b32 s9, s18, 2
	s_add_i32 s9, s9, 0
	s_add_i32 s9, s9, 0x18000
	v_writelane_b32 v245, s9, 26
	s_add_i32 s10, s64, 0x4000
	v_writelane_b32 v245, s10, 27
	s_add_i32 s10, s64, 0x6000
	v_writelane_b32 v245, s10, 28
	s_add_i32 s10, s64, 0x8000
	v_writelane_b32 v245, s10, 29
	s_add_i32 s10, s64, 0xa000
	v_writelane_b32 v245, s10, 30
	s_add_i32 s10, s83, 0xffffffb0
	v_writelane_b32 v245, s10, 31
	s_or_b32 s10, s4, 0x100
	v_writelane_b32 v245, s10, 32
	s_lshl_b32 s10, s18, 13
	v_writelane_b32 v245, s10, 33
	s_mul_i32 s10, s18, 0x1c00
	s_add_i32 s65, s64, s10
	s_add_i32 s10, s65, 0x10000
	v_writelane_b32 v245, s10, 34
	s_add_i32 s10, s65, 0x10400
	v_writelane_b32 v245, s10, 35
	s_add_i32 s10, s65, 0x10800
	v_writelane_b32 v245, s10, 36
	s_add_i32 s10, s65, 0x10c00
	v_writelane_b32 v245, s10, 37
	s_add_i32 s10, s65, 0x11000
	v_writelane_b32 v245, s10, 38
	s_add_i32 s10, s65, 0x11400
	v_writelane_b32 v245, s10, 39
	s_add_i32 s10, s65, 0x11800
	v_writelane_b32 v245, s10, 40
	s_add_i32 s10, s65, 0x11c00
	v_writelane_b32 v245, s10, 41
	s_mul_i32 s10, s18, 0xffffe002
	s_add_i32 s10, s65, s10
	v_writelane_b32 v245, s10, 42
	s_mul_i32 s10, s18, 14
	s_and_b32 s10, s10, 14
	s_add_i32 s10, s63, s10
	v_writelane_b32 v245, s10, 43
	s_mulk_i32 s5, 0x160
	s_add_i32 s13, s4, 3
	v_writelane_b32 v245, s5, 44
	s_or_b32 s5, s5, s82
	s_lshl_b32 s14, s13, 6
	s_mul_hi_u32 s11, s5, 0x5d1745e
	s_lshr_b32 s11, s11, 2
	s_and_b32 s33, s14, 0x1c0
	s_add_i32 s14, s4, 4
	s_lshl_b32 s12, s11, 3
	s_mul_i32 s11, s11, 176
	s_lshl_b32 s15, s14, 6
	s_sub_i32 s5, s5, s11
	s_and_b32 s11, s6, 1
	s_and_b32 s46, s15, 0x1c0
	s_add_i32 s15, s4, 5
	s_or_b32 s8, s11, s8
	s_lshl_b32 s16, s15, 6
	v_writelane_b32 v245, s8, 45
	s_lshl_b32 s8, s8, 19
	s_and_b32 s47, s16, 0x1c0
	s_add_i32 s16, s4, 6
	s_add_i32 s53, s4, 1
	v_writelane_b32 v245, s8, 46
	s_add_i32 s8, s4, 2
	s_lshl_b32 s17, s16, 6
	s_add_i32 s4, s4, 7
	s_lshr_b32 s6, s6, 1
	s_and_b32 s48, s17, 0x1c0
	s_lshl_b32 s17, s4, 6
	v_writelane_b32 v245, s6, 47
	s_lshl_b32 s6, s6, 19
	s_and_b32 s49, s17, 0x1c0
	s_bfe_i32 s17, s53, 0x10002
	v_writelane_b32 v245, s6, 48
	s_lshl_b32 s11, s8, 6
	s_addk_i32 s17, 0xa1
	s_bfe_i32 s8, s8, 0x10002
	v_writelane_b32 v245, s17, 49
	s_addk_i32 s8, 0xa1
	v_writelane_b32 v245, s8, 50
	s_bfe_i32 s8, s13, 0x10002
	s_addk_i32 s8, 0xa1
	v_writelane_b32 v245, s8, 51
	s_bfe_i32 s8, s14, 0x10002
	s_addk_i32 s8, 0xa1
	v_writelane_b32 v245, s8, 52
	s_bfe_i32 s8, s15, 0x10002
	s_addk_i32 s8, 0xa1
	s_or_b32 s10, s3, s82
	v_writelane_b32 v245, s8, 53
	s_bfe_i32 s8, s16, 0x10002
	s_lshr_b32 s10, s10, 2
	s_addk_i32 s8, 0xa1
	s_bfe_i32 s4, s4, 0x10002
	s_and_b32 s10, s10, 62
	v_writelane_b32 v245, s8, 54
	s_addk_i32 s4, 0xa1
	v_writelane_b32 v245, s4, 55
	s_or_b32 s4, s7, s10
	s_bfe_u32 s2, s2, 0x20004
	v_writelane_b32 v245, s4, 56
	s_lshl_b32 s4, s4, 19
	v_writelane_b32 v245, s4, 57
	s_lshl_b32 s4, s2, 19
	v_writelane_b32 v245, s4, 58
	v_writelane_b32 v245, s2, 59
	s_lshl_b32 s2, s2, 8
	v_writelane_b32 v245, s2, 60
	s_and_b32 s2, s5, 7
	s_or_b32 s2, s2, s12
	s_lshr_b32 s4, s5, 3
	v_writelane_b32 v245, s2, 61
	s_lshl_b32 s2, s2, 19
	v_writelane_b32 v245, s2, 62
	s_lshl_b32 s2, s4, 19
	s_lshl_b32 s6, s53, 6
	v_writelane_b32 v244, s2, 0
	s_lshl_b32 s2, s83, 7
	v_writelane_b32 v244, s2, 1
	s_or_b32 s2, s19, 0x540080
	v_writelane_b32 v244, s2, 2
	s_add_i32 s2, s82, s83
	s_lshl_b32 s2, s2, 18
	s_lshr_b32 s9, s83, 2
	s_and_b32 s6, s6, 0x1c0
	s_and_b32 s11, s11, 0x1c0
	s_and_b32 s2, s2, 0x7f80000
	s_add_u32 s2, s2, 0x7200100
	v_writelane_b32 v244, s2, 3
	s_addc_u32 s2, 0, 0
	v_writelane_b32 v244, s2, 4
	s_lshl_b32 s2, s18, 7
	s_add_i32 s82, s82, s3
	v_writelane_b32 v244, s2, 5
	s_bfe_u32 s2, s82, 0x50003
	s_lshl_b32 s3, s2, 20
	s_or_b32 s3, s3, s19
	v_writelane_b32 v244, s19, 6
	s_add_u32 s3, s3, 0xb240080
	s_mul_i32 s2, s2, 0x2c0000
	s_mul_i32 s7, s7, 0x160000
	v_writelane_b32 v244, s3, 7
	s_addc_u32 s3, 0, 0
	s_add_i32 s2, s2, s7
	v_writelane_b32 v244, s3, 8
	s_add_u32 s2, s2, 0x132b0080
	v_writelane_b32 v244, s2, 9
	s_addc_u32 s2, 0, 0
	v_writelane_b32 v244, s2, 10
	s_lshl_b32 s2, s9, 2
	v_writelane_b32 v244, s2, 11
	s_lshl_b32 s2, s6, 2
	v_writelane_b32 v244, s2, 12
	s_lshl_b32 s2, s11, 2
	v_writelane_b32 v244, s2, 13
	s_lshl_b32 s2, s33, 2
	v_writelane_b32 v244, s2, 14
	s_lshl_b32 s2, s46, 2
	v_writelane_b32 v244, s2, 15
	s_lshl_b32 s2, s47, 2
	v_writelane_b32 v244, s2, 16
	s_lshl_b32 s2, s48, 2
	v_writelane_b32 v244, s2, 17
	s_lshl_b32 s2, s49, 2
	v_writelane_b32 v244, s2, 18
	s_add_i32 s2, 0, 0x24020
	v_writelane_b32 v244, s2, 19
	s_add_i32 s2, 0, 0x24024
	v_writelane_b32 v244, s2, 20
	s_add_i32 s2, 0, 0x18010
	v_writelane_b32 v244, s2, 21
	s_mov_b64 s[2:3], 0
	v_writelane_b32 v244, s2, 22
	s_mov_b32 s14, 2.0
	s_mov_b32 s16, 0x41000000
	v_writelane_b32 v244, s3, 23
	s_mov_b32 s18, 0x41200000
	s_mov_b32 s20, 0x41800000
	s_mov_b32 s22, 0x41900000
	s_mov_b32 s24, 0x41c00000
	s_mov_b32 s26, 0x41d00000
	s_mov_b32 s28, 0x42680000
	s_mov_b32 s30, 0x42600000
	s_mov_b32 s34, 0x42480000
	s_mov_b32 s36, 0x42400000
	s_mov_b32 s38, 0x42280000
	s_mov_b32 s40, 0x42200000
	s_mov_b32 s42, 0x42080000
	s_mov_b32 s44, 0x42000000
	v_writelane_b32 v244, s76, 24
	v_writelane_b32 v245, s4, 63
	v_mov_b32_e32 v1, 0
	v_mov_b32_e32 v227, 0x1000
	v_mov_b32_e32 v228, 0x2000
	v_mov_b32_e32 v229, 0x7000
	v_mov_b32_e32 v230, 1
	v_mov_b32_e32 v231, 0x3f4ccccd
	v_mov_b32_e32 v232, 0x260
	s_mov_b32 s15, 0x40400000
	s_mov_b32 s17, 0x41100000
	s_mov_b32 s19, 0x41300000
	s_mov_b32 s21, 0x41880000
	s_mov_b32 s23, 0x41980000
	s_mov_b32 s25, 0x41c80000
	s_mov_b32 s27, 0x41d80000
	s_mov_b32 s29, 0x426c0000
	s_mov_b32 s31, 0x42640000
	s_mov_b32 s35, 0x424c0000
	s_mov_b32 s37, 0x42440000
	s_mov_b32 s39, 0x422c0000
	s_mov_b32 s41, 0x42240000
	s_mov_b32 s43, 0x420c0000
	s_mov_b32 s45, 0x42040000
	v_mov_b32_e32 v233, 0x3727c5ac
	v_mov_b32_e32 v234, 0x7f800000
	v_mov_b32_e32 v235, 0x3fb8aa3b
	v_mov_b32_e32 v236, 0xa0
	v_mov_b32_e32 v237, 0xa1
	v_mov_b64_e32 v[190:191], 0x1e8481
	v_mov_b32_e32 v238, 0x7fc00000
	s_movk_i32 s48, 0xc00
	s_movk_i32 s49, 0x7fff
	s_add_i32 s90, 0, 0x18100
	s_movk_i32 s62, 0x1600
	s_mov_b32 s46, 0
	s_mov_b32 s47, 0
	s_mov_b64 s[4:5], -1
	s_mov_b64 s[50:51], 0x80
	s_mov_b32 s54, 0x3c800000
	s_mov_b32 s66, 0x3fb504f3
	v_writelane_b32 v244, s77, 25
	v_writelane_b32 v244, s90, 26
	s_branch .LBB0_157

.LBB0_880:
	s_add_i32 s88, s89, 1
	s_cmp_lt_u32 s89, 10
	s_cselect_b64 s[12:13], -1, 0
	s_cmp_gt_u32 s89, 9
	s_cbranch_scc1 .LBB0_882
	s_lshl_b32 s8, s88, 8
	v_readlane_b32 s9, v245, 3
	s_or_b32 s8, s8, s9
	s_lshr_b32 s8, s8, 3
	v_readlane_b32 s9, v245, 44
	s_add_i32 s8, s8, s9
	s_mul_hi_u32 s9, s8, 0xba2e8ba3
	s_lshr_b32 s9, s9, 7
	s_lshl_b32 s55, s9, 3
	s_mul_i32 s9, s9, 176
	s_sub_i32 s9, s8, s9
	s_and_b32 s8, s9, 7
	s_or_b32 s8, s8, s55
	s_lshr_b32 s74, s9, 3
